# baseline (speedup 1.0000x reference)
; __device__ __forceinline__ void scan_pc(const Params& p, int j, const u16* R, const u16* K, const u16* V, u16* Y, u16* YB) {
;     ...
;       _Pragma("unroll") for (int kb = 0; kb < 4; ++kb) {
;         s4 xa = *reinterpret_cast<const s4*>(IMG + (ai * 16 + fr) * XT_LD + kb * 16 + fq * 4);
;         s4 xb = *reinterpret_cast<const s4*>(IMG + (bi * 16 + fr) * XT_LD + kb * 16 + fq * 4);
;         mt = MFMA4(xb, xa, mt);
;         if (w4 == 0) nc = MFMA4(xa, xb, nc);
;       }
;       float* SSQ = reinterpret_cast<float*>(IMG + IMG_PL) + 128;
;     ...
;       const u16* IMG = shm + (c % 3) * IMG_ELEMS;
;       const u16* MM = shm + 4 * IMG_ELEMS + (c & 1) * MM_ELEMS;
;       s4 vb = *reinterpret_cast<const s4*>(IMG + IMG_VT + (w4 * 16 + fr) * XK_LD + fq * 4);
;       f32x4 z4 = {0.f, 0.f, 0.f, 0.f};
;       const float* PL = reinterpret_cast<const float*>(IMG + IMG_PL);
;       float4 iv = *reinterpret_cast<const float4*>(PL + 192 + fq * 4);
;       f32x4 rhs = z4;
;       f32x4 y = MFMA4(*reinterpret_cast<const s4*>(MM + (3 * 16 + fr) * XK_LD + fq * 4), vb, z4);
;       _Pragma("unroll") for (int kb = 0; kb < 4; ++kb) {
;         rhs = MFMA4(*reinterpret_cast<const s4*>(IMG + (0 * 16 + fr) * XT_LD + kb * 16 + fq * 4), Zb[kb], rhs);
;         y = MFMA4(*reinterpret_cast<const s4*>(IMG + (1 * 16 + fr) * XT_LD + kb * 16 + fq * 4), Zb[kb], y);
;       }
;       rhs[0] *= iv.x; rhs[1] *= iv.y; rhs[2] *= iv.z; rhs[3] *= iv.w;
;       rhs = MFMA4(*reinterpret_cast<const s4*>(MM + (1 * 16 + fr) * XK_LD + fq * 4), vb, rhs);
;       f32x4 u = MFMA4(*reinterpret_cast<const s4*>(MM + (0 * 16 + fr) * XK_LD + fq * 4), pack4v(rhs), z4);
;       y = MFMA4(*reinterpret_cast<const s4*>(MM + (2 * 16 + fr) * XK_LD + fq * 4), pack4v(u), y);
;       s4 ub = pack4(u[0] * iv.x, u[1] * iv.y, u[2] * iv.z, u[3] * iv.w);
;       _Pragma("unroll") for (int kb = 0; kb < 4; ++kb) {
;         Z[kb] = MFMA4(*reinterpret_cast<const s4*>(IMG + IMG_XK + (0 * 64 + kb * 16 + fr) * XK_LD + fq * 4), ub, Z[kb]);
;         Z[kb] = MFMA4(*reinterpret_cast<const s4*>(IMG + IMG_XK + (1 * 64 + kb * 16 + fr) * XK_LD + fq * 4), vb, Z[kb]);
;         float4 pl = *reinterpret_cast<const float4*>(PL + kb * 16 + fq * 4);
;         Z[kb][0] *= pl.x; Z[kb][1] *= pl.y; Z[kb][2] *= pl.z; Z[kb][3] *= pl.w;
;         Zb[kb] = pack4v(Z[kb]);
;       }
.LBB0_2720:
	s_mul_hi_u32 s26, s28, 0xaaaaaaab
	s_lshr_b32 s26, s26, 1
	s_mul_i32 s26, s26, 3
	s_sub_i32 s75, 1, s26
	v_lshlrev_b32_e32 v179, 1, v97
	s_and_saveexec_b64 s[26:27], s[10:11]
	s_xor_b64 s[26:27], exec, s[26:27]
	s_cbranch_execz .LBB0_2739
	s_mov_b32 s30, 0xaaaaaaab
	v_mul_hi_u32 v50, v90, s30
	v_lshrrev_b32_e32 v50, 1, v50
	v_mad_u64_u32 v[50:51], s[30:31], v50, -3, v[90:91]
	v_mad_u32_u24 v58, v50, s80, 0
	v_add3_u32 v50, v58, v127, v179
	ds_read_b64 v[70:71], v50 offset:14336
	v_lshl_add_u32 v50, v97, 2, v58
	ds_read_b128 v[66:69], v50 offset:17664
	v_add3_u32 v50, v58, v146, v179
	ds_read2_b64 v[60:63], v145 offset0:160 offset1:240
	ds_read2_b64 v[194:197], v50 offset1:4
	v_add_u32_e32 v59, 0x800, v50
	ds_read2_b64 v[202:205], v59 offset0:32 offset1:36
	v_add_u32_e32 v225, s75, v90
	v_mad_u32_u24 v225, v225, s80, 0
	v_add3_u32 v226, v225, v136, v179
	v_add3_u32 v227, v225, v134, v179
	ds_read_b64 v[234:235], v226
	ds_read_b64 v[236:237], v227
	ds_read_b64 v[206:207], v226 offset:32
	ds_read_b64 v[208:209], v227 offset:32
	ds_read_b64 v[210:211], v226 offset:64
	ds_read_b64 v[212:213], v227 offset:64
	ds_read_b64 v[214:215], v226 offset:96
	ds_read_b64 v[216:217], v227 offset:96
	v_lshl_add_u32 v218, v96, 2, v225
	v_add_u32_e32 v219, 0x4400, v218
	ds_read2_b32 v[220:221], v219 offset1:16
	ds_read2_b32 v[222:223], v219 offset0:32 offset1:48
	s_waitcnt lgkmcnt(12)
	v_mfma_f32_16x16x16_bf16 v[92:95], v[62:63], v[70:71], 0
	v_add3_u32 v91, v58, v144, v133
	v_add_u32_e32 v193, 0x2c00, v91
	v_readlane_b32 s76, v247, 14
	s_waitcnt lgkmcnt(11)
	v_mfma_f32_16x16x16_bf16 v[198:201], v[194:195], v[64:65], 0
	v_readlane_b32 s77, v247, 15
	v_readlane_b32 s78, v247, 16
	v_readlane_b32 s79, v247, 17
	s_waitcnt lgkmcnt(10)
	v_mfma_f32_16x16x16_bf16 v[62:65], v[202:203], v[64:65], v[92:95]
	s_mov_b32 s77, s76
	s_mov_b32 s78, s76
	s_mov_b32 s79, s76
	v_mfma_f32_16x16x16_bf16 v[92:95], v[196:197], v[56:57], v[198:201]
	ds_read2_b64 v[194:197], v50 offset0:8 offset1:12
	v_add_u32_e32 v50, 0x2000, v91
	v_writelane_b32 v247, s76, 14
	s_waitcnt lgkmcnt(0)
	v_mfma_f32_16x16x16_bf16 v[92:95], v[194:195], v[52:53], v[92:95]
	ds_read2_b64 v[198:201], v145 offset1:80
	v_writelane_b32 v247, s77, 15
	v_writelane_b32 v247, s78, 16
	v_mfma_f32_16x16x16_bf16 v[92:95], v[196:197], v[48:49], v[92:95]
	ds_read2_b64 v[194:197], v50 offset0:128 offset1:208
	v_writelane_b32 v247, s79, 17
	v_mfma_f32_16x16x16_bf16 v[62:65], v[204:205], v[56:57], v[62:65]
	s_nop 4
	v_mul_f32_e64 v94, v68, v94
	v_mul_f32_e64 v95, v69, v95
	v_pk_mul_f32 v[92:93], v[66:67], v[92:93]
	s_waitcnt lgkmcnt(1)
	s_nop 0
	v_mfma_f32_16x16x16_bf16 v[92:95], v[200:201], v[70:71], v[92:95]
	s_nop 7
	v_cvt_pk_bf16_f32 v50, v92, v93
	v_cvt_pk_bf16_f32 v51, v94, v95
	s_nop 1
	v_mfma_f32_16x16x16_bf16 v[92:95], v[198:199], v[50:51], 0
	ds_read2_b64 v[198:201], v59 offset0:40 offset1:44
	s_nop 6
	v_pk_mul_f32 v[50:51], v[66:67], v[92:93]
	v_pk_mul_f32 v[54:55], v[68:69], v[94:95]
	ds_read2_b64 v[66:69], v193 offset0:64 offset1:144
	v_cvt_pk_bf16_f32 v180, v50, v51
	v_cvt_pk_bf16_f32 v181, v54, v55
	s_waitcnt lgkmcnt(1)
	v_mfma_f32_16x16x16_bf16 v[50:53], v[198:199], v[52:53], v[62:65]
	v_add_u32_e32 v193, v58, v112
	v_add_u32_e32 v54, 0x2800, v91
	v_cvt_pk_bf16_f32 v202, v92, v93
	v_mfma_f32_16x16x16_bf16 v[40:43], v[194:195], v[180:181], v[40:43]
	v_cvt_pk_bf16_f32 v203, v94, v95
	v_mfma_f32_16x16x16_bf16 v[194:197], v[196:197], v[180:181], v[44:47]
	ds_read_b128 v[56:59], v193 offset:16896
	s_nop 1
	ds_read_b128 v[44:47], v193 offset:16960
	s_waitcnt lgkmcnt(2)
	v_mfma_f32_16x16x16_bf16 v[40:43], v[66:67], v[70:71], v[40:43]
	ds_read2_b64 v[64:67], v54 offset0:32 offset1:112
	v_add_u32_e32 v54, 0x3000, v91
	v_add_u32_e32 v91, s74, v166
	v_mfma_f32_16x16x16_bf16 v[92:95], v[200:201], v[48:49], v[50:53]
	ds_read2_b64 v[198:201], v54 offset0:96 offset1:176
	s_nop 1
	ds_read_b128 v[52:55], v193 offset:17024
	ds_read_b128 v[48:51], v193 offset:17088
	v_mfma_f32_16x16x16_bf16 v[92:95], v[60:61], v[202:203], v[92:95]
	s_waitcnt lgkmcnt(3)
	v_mfma_f32_16x16x16_bf16 v[32:35], v[64:65], v[180:181], v[32:35]
	v_mfma_f32_16x16x16_bf16 v[36:39], v[66:67], v[180:181], v[36:39]
	s_andn2_b64 vcc, exec, s[20:21]
	s_cbranch_vccnz .Lyold_done_a
	s_waitcnt vmcnt(0)
	v_lshlrev_b32_e32 v87, 16, v230
	v_lshlrev_b32_e32 v88, 16, v231
	v_lshlrev_b32_e32 v86, 16, v232
	v_lshlrev_b32_e32 v89, 16, v233
; #define MFMA4(a, b, c) __builtin_amdgcn_mfma_f32_16x16x16bf16_1k(a, b, c, 0, 0, 0)
; __device__ __forceinline__ void scan_pc(const Params& p, int j, const u16* R, const u16* K, const u16* V, u16* Y, u16* YB) {
;     ...
;       u16* IMG = shm + (c % 3) * IMG_ELEMS;
;       u16* MM = shm + 4 * IMG_ELEMS + (c & 1) * MM_ELEMS;
;       int ai = (w4 < 2) ? 0 : 1, bi = (w4 & 1) ? 3 : 2;
;       f32x4 mt = {0.f, 0.f, 0.f, 0.f}, nc = {0.f, 0.f, 0.f, 0.f};
;       _Pragma("unroll") for (int kb = 0; kb < 4; ++kb) {
;         s4 xa = *reinterpret_cast<const s4*>(IMG + (ai * 16 + fr) * XT_LD + kb * 16 + fq * 4);
;         s4 xb = *reinterpret_cast<const s4*>(IMG + (bi * 16 + fr) * XT_LD + kb * 16 + fq * 4);
;         mt = MFMA4(xb, xa, mt);
;         if (w4 == 0) nc = MFMA4(xa, xb, nc);
;       }
;       float* SSQ = reinterpret_cast<float*>(IMG + IMG_PL) + 128;
;       float inv_t = rsqrtf(fmaxf((SSQ[fr] + SSQ[16 + fr]) + (SSQ[32 + fr] + SSQ[48 + fr]), 1e-24f));
;       if (w4 == 3) SSQ[64 + fr] = inv_t;
;       float ivr = (w4 < 2) ? inv_t : 1.f;
;       float sc_[4];
;       _Pragma("unroll") for (int jj = 0; jj < 4; ++jj) {
;         float ivj = __builtin_bit_cast(float, __builtin_amdgcn_ds_bpermute(((lane & 48) | (fq * 4 + jj)) << 2, __builtin_bit_cast(int, inv_t)));
;         sc_[jj] = ivr * (((w4 & 1) == 0) ? ivj : 1.f);
;         mt[jj] *= sc_[jj] * keepm[jj];
;       }
;       if (w4 == 0) {
;         _Pragma("unroll") for (int jj = 0; jj < 4; ++jj) nc[jj] *= sc_[jj] * keepn[jj];
;         f32x4 z4 = {0.f, 0.f, 0.f, 0.f};
;         s4 pN = pack4v(nc), pNT = pack4v(mt);
;         f32x4 n2 = MFMA4(pNT, pN, z4);
;         f32x4 n2t = MFMA4(pN, pNT, z4);
;         s4 pN2 = pack4v(n2), pN2T = pack4v(n2t);
;         f32x4 n4 = MFMA4(pN2T, pN2, z4);
;         f32x4 n4t = MFMA4(pN2, pN2T, z4);
;         s4 pN4 = pack4v(n4), pN4T = pack4v(n4t);
;         f32x4 n8 = MFMA4(pN4T, pN4, z4);
;         s4 pN8 = pack4v(n8);
;         f32x4 tt = mt;
;         _Pragma("unroll") for (int jj = 0; jj < 4; ++jj) tt[jj] += diagm[jj];
;         tt = MFMA4(pN2, pack4v(tt), tt);
;         tt = MFMA4(pN4, pack4v(tt), tt);
;         tt = MFMA4(pN8, pack4v(tt), tt);
;         mt = tt;
;     ...
;       _Pragma("unroll") for (int jj = 0; jj < 4; ++jj)
;         sto<u16>(Yw, (unsigned)(offK0[jj] + c * dK), f2b(ymode == 1 ? y[jj] + yo[jj] : y[jj]));
.Lyold_done_a:
	s_nop 4
	v_add_f32_e32 v60, v87, v92
	v_cndmask_b32_e64 v92, v92, v60, s[20:21]
	v_add_f32_e32 v64, v86, v93
	v_mfma_f32_16x16x16_bf16 v[60:63], v[68:69], v[70:71], v[194:197]
	v_cvt_pk_bf16_f32 v68, v92, s0
	v_cndmask_b32_e64 v64, v93, v64, s[20:21]
	v_add_f32_e32 v65, v89, v94
	global_store_short v91, v68, s[70:71]
	v_add_u32_e32 v68, s74, v178
	v_cvt_pk_bf16_f32 v64, v64, s0
	v_cndmask_b32_e64 v65, v94, v65, s[20:21]
	global_store_short v68, v64, s[70:71]
	v_add_u32_e32 v64, s74, v177
	v_cvt_pk_bf16_f32 v65, v65, s0
	global_store_short v64, v65, s[70:71]
	v_add_f32_e32 v64, v88, v95
	s_waitcnt lgkmcnt(2)
	v_mfma_f32_16x16x16_bf16 v[32:35], v[198:199], v[70:71], v[32:35]
	v_cndmask_b32_e64 v64, v95, v64, s[20:21]
	v_add_u32_e32 v65, s74, v176
	v_cvt_pk_bf16_f32 v64, v64, s0
	v_mfma_f32_16x16x16_bf16 v[36:39], v[200:201], v[70:71], v[36:39]
	global_store_short v65, v64, s[70:71]
	v_add_u32_e32 v64, 1, v90
	v_cmp_gt_u32_e32 vcc, s2, v64
	s_and_saveexec_b64 s[62:63], vcc
	s_cbranch_execz .LBB0_2738
	v_add_u32_e32 v64, s75, v90
	v_mad_u32_u24 v91, v64, s80, 0
	v_readlane_b32 s76, v247, 14
	v_readlane_b32 s77, v247, 15
	v_readlane_b32 s78, v247, 16
	v_readlane_b32 s79, v247, 17
	v_mov_b64_e32 v[68:69], s[76:77]
	s_waitcnt lgkmcnt(0)
	v_mfma_f32_16x16x16_bf16 v[64:67], v[234:235], v[236:237], 0
	v_mov_b64_e32 v[70:71], s[78:79]
	s_and_saveexec_b64 s[30:31], s[14:15]
	v_mfma_f32_16x16x16_bf16 v[68:71], v[236:237], v[234:235], 0
	s_or_b64 exec, exec, s[30:31]
	v_mfma_f32_16x16x16_bf16 v[64:67], v[206:207], v[208:209], v[64:67]
	s_and_saveexec_b64 s[30:31], s[14:15]
	v_mfma_f32_16x16x16_bf16 v[68:71], v[208:209], v[206:207], v[68:71]
	s_or_b64 exec, exec, s[30:31]
	v_mfma_f32_16x16x16_bf16 v[64:67], v[210:211], v[212:213], v[64:67]
	s_and_saveexec_b64 s[30:31], s[14:15]
	v_mfma_f32_16x16x16_bf16 v[68:71], v[212:213], v[210:211], v[68:71]
	s_or_b64 exec, exec, s[30:31]
	v_mfma_f32_16x16x16_bf16 v[64:67], v[214:215], v[216:217], v[64:67]
	s_and_saveexec_b64 s[30:31], s[14:15]
	v_mfma_f32_16x16x16_bf16 v[68:71], v[216:217], v[214:215], v[68:71]
	s_or_b64 exec, exec, s[30:31]
	v_lshl_add_u32 v93, v96, 2, v91
	s_waitcnt lgkmcnt(0)
	v_add_f32_e32 v180, v220, v221
	v_add_f32_e32 v92, v222, v223
	v_add_f32_e32 v92, v180, v92
	v_max_f32_e32 v92, 0x179abe15, v92
	v_rsq_f32_e32 v92, v92
	s_and_saveexec_b64 s[30:31], s[16:17]
	ds_write_b32 v93, v92 offset:17664
	s_or_b64 exec, exec, s[30:31]
	ds_bpermute_b32 v93, v138, v92
	ds_bpermute_b32 v94, v139, v92
	v_cndmask_b32_e64 v95, 1.0, v92, s[6:7]
	ds_bpermute_b32 v180, v140, v92
	ds_bpermute_b32 v224, v141, v92
	s_waitcnt lgkmcnt(3)
	v_cndmask_b32_e64 v93, 1.0, v93, s[18:19]
	s_waitcnt lgkmcnt(2)
	v_cndmask_b32_e64 v94, 1.0, v94, s[18:19]
	v_mul_f32_e32 v93, v95, v93
	v_mul_f32_e32 v181, v98, v93
	v_mul_f32_e32 v94, v95, v94
	v_mul_f32_e32 v64, v64, v181
	v_mul_f32_e32 v181, v101, v94
	v_mul_f32_e32 v65, v65, v181
	s_waitcnt lgkmcnt(1)
	v_cndmask_b32_e64 v92, 1.0, v180, s[18:19]
	v_mul_f32_e32 v92, v95, v92
	v_mul_f32_e32 v180, v104, v92
	v_mul_f32_e32 v66, v66, v180
	s_waitcnt lgkmcnt(0)
	v_cndmask_b32_e64 v180, 1.0, v224, s[18:19]
	v_mul_f32_e32 v95, v95, v180
	v_mul_f32_e32 v180, v107, v95
	v_mul_f32_e32 v67, v67, v180
	s_and_saveexec_b64 s[30:31], s[14:15]
	s_cbranch_execz .LBB0_2734
	v_mul_f32_e32 v93, v99, v93
	v_mul_f32_e32 v92, v105, v92
	v_mul_f32_e32 v68, v68, v93
	v_mul_f32_e32 v93, v102, v94
	v_mul_f32_e32 v70, v70, v92
	v_mul_f32_e32 v92, v108, v95
	v_mul_f32_e32 v69, v69, v93
	v_mul_f32_e32 v71, v71, v92
	v_cvt_pk_bf16_f32 v92, v68, v69
	v_cvt_pk_bf16_f32 v93, v70, v71
	v_cvt_pk_bf16_f32 v94, v64, v65
	v_cvt_pk_bf16_f32 v95, v66, v67
	v_add_f32_e32 v64, v100, v64
	v_add_f32_e32 v65, v103, v65
	v_mfma_f32_16x16x16_bf16 v[68:71], v[94:95], v[92:93], 0
	v_add_f32_e32 v66, v106, v66
	v_add_f32_e32 v67, v109, v67
	v_mfma_f32_16x16x16_bf16 v[92:95], v[92:93], v[94:95], 0
	s_nop 4
	v_cvt_pk_bf16_f32 v180, v68, v69
	v_cvt_pk_bf16_f32 v181, v70, v71
	s_nop 0
	v_cvt_pk_bf16_f32 v92, v92, v93
	v_cvt_pk_bf16_f32 v93, v94, v95
	s_nop 1
	v_mfma_f32_16x16x16_bf16 v[68:71], v[92:93], v[180:181], 0
	v_mfma_f32_16x16x16_bf16 v[92:95], v[180:181], v[92:93], 0
	s_nop 6
	v_cvt_pk_bf16_f32 v194, v68, v69
	v_cvt_pk_bf16_f32 v195, v70, v71
	v_cvt_pk_bf16_f32 v68, v92, v93
	v_cvt_pk_bf16_f32 v69, v94, v95
	s_nop 1
	v_mfma_f32_16x16x16_bf16 v[68:71], v[68:69], v[194:195], 0
	s_nop 7
	v_cvt_pk_bf16_f32 v68, v68, v69
	v_cvt_pk_bf16_f32 v69, v70, v71
	v_cvt_pk_bf16_f32 v70, v64, v65
	v_cvt_pk_bf16_f32 v71, v66, v67
	s_nop 1
	v_mfma_f32_16x16x16_bf16 v[64:67], v[180:181], v[70:71], v[64:67]
	s_nop 7
	v_cvt_pk_bf16_f32 v70, v64, v65
	v_cvt_pk_bf16_f32 v71, v66, v67
	s_nop 1
	v_mfma_f32_16x16x16_bf16 v[64:67], v[194:195], v[70:71], v[64:67]
	s_nop 7
	v_cvt_pk_bf16_f32 v70, v64, v65
	v_cvt_pk_bf16_f32 v71, v66, v67
	s_nop 1
	v_mfma_f32_16x16x16_bf16 v[64:67], v[68:69], v[70:71], v[64:67]

; __device__ __forceinline__ void scan_pc(const Params& p, int j, const u16* R, const u16* K, const u16* V, u16* Y, u16* YB) {
;     ...
;       _Pragma("unroll") for (int kb = 0; kb < 4; ++kb) {
;         s4 xa = *reinterpret_cast<const s4*>(IMG + (ai * 16 + fr) * XT_LD + kb * 16 + fq * 4);
;         s4 xb = *reinterpret_cast<const s4*>(IMG + (bi * 16 + fr) * XT_LD + kb * 16 + fq * 4);
;         mt = MFMA4(xb, xa, mt);
;         if (w4 == 0) nc = MFMA4(xa, xb, nc);
;       }
;       float* SSQ = reinterpret_cast<float*>(IMG + IMG_PL) + 128;
;     ...
;       const u16* IMG = shm + (c % 3) * IMG_ELEMS;
;       const u16* MM = shm + 4 * IMG_ELEMS + (c & 1) * MM_ELEMS;
;       s4 vb = *reinterpret_cast<const s4*>(IMG + IMG_VT + (w4 * 16 + fr) * XK_LD + fq * 4);
;       f32x4 z4 = {0.f, 0.f, 0.f, 0.f};
;       const float* PL = reinterpret_cast<const float*>(IMG + IMG_PL);
;       float4 iv = *reinterpret_cast<const float4*>(PL + 192 + fq * 4);
;       f32x4 rhs = z4;
;       f32x4 y = MFMA4(*reinterpret_cast<const s4*>(MM + (3 * 16 + fr) * XK_LD + fq * 4), vb, z4);
;       _Pragma("unroll") for (int kb = 0; kb < 4; ++kb) {
;         rhs = MFMA4(*reinterpret_cast<const s4*>(IMG + (0 * 16 + fr) * XT_LD + kb * 16 + fq * 4), Zb[kb], rhs);
;         y = MFMA4(*reinterpret_cast<const s4*>(IMG + (1 * 16 + fr) * XT_LD + kb * 16 + fq * 4), Zb[kb], y);
;       }
;       rhs[0] *= iv.x; rhs[1] *= iv.y; rhs[2] *= iv.z; rhs[3] *= iv.w;
;       rhs = MFMA4(*reinterpret_cast<const s4*>(MM + (1 * 16 + fr) * XK_LD + fq * 4), vb, rhs);
;       f32x4 u = MFMA4(*reinterpret_cast<const s4*>(MM + (0 * 16 + fr) * XK_LD + fq * 4), pack4v(rhs), z4);
;       y = MFMA4(*reinterpret_cast<const s4*>(MM + (2 * 16 + fr) * XK_LD + fq * 4), pack4v(u), y);
;       s4 ub = pack4(u[0] * iv.x, u[1] * iv.y, u[2] * iv.z, u[3] * iv.w);
;       _Pragma("unroll") for (int kb = 0; kb < 4; ++kb) {
;         Z[kb] = MFMA4(*reinterpret_cast<const s4*>(IMG + IMG_XK + (0 * 64 + kb * 16 + fr) * XK_LD + fq * 4), ub, Z[kb]);
;         Z[kb] = MFMA4(*reinterpret_cast<const s4*>(IMG + IMG_XK + (1 * 64 + kb * 16 + fr) * XK_LD + fq * 4), vb, Z[kb]);
;         float4 pl = *reinterpret_cast<const float4*>(PL + kb * 16 + fq * 4);
;         Z[kb][0] *= pl.x; Z[kb][1] *= pl.y; Z[kb][2] *= pl.z; Z[kb][3] *= pl.w;
;         Zb[kb] = pack4v(Z[kb]);
;       }
.LBB0_2745:
	s_or_b64 exec, exec, s[26:27]
	s_waitcnt lgkmcnt(0)
	s_barrier
	s_and_saveexec_b64 s[26:27], s[10:11]
	s_xor_b64 s[26:27], exec, s[26:27]
	s_cbranch_execz .LBB0_2764
	v_add_u32_e32 v50, s75, v90
	v_mad_u32_u24 v91, v50, s80, 0
	v_add3_u32 v51, v91, v146, v179
	ds_read2_b64 v[66:69], v147 offset0:160 offset1:240
	ds_read2_b64 v[92:95], v51 offset1:4
	v_add3_u32 v50, v91, v127, v179
	ds_read_b64 v[180:181], v50 offset:14336
	v_lshl_add_u32 v50, v97, 2, v91
	ds_read_b128 v[58:61], v50 offset:17664
	v_add_u32_e32 v50, 0x800, v51
	ds_read2_b64 v[198:201], v50 offset0:32 offset1:36
	v_add_u32_e32 v225, s76, v90
	v_mad_u32_u24 v225, v225, s80, 0
	v_add3_u32 v226, v225, v136, v179
	v_add3_u32 v227, v225, v134, v179
	ds_read_b64 v[234:235], v226
	ds_read_b64 v[236:237], v227
	ds_read_b64 v[206:207], v226 offset:32
	ds_read_b64 v[208:209], v227 offset:32
	ds_read_b64 v[210:211], v226 offset:64
	ds_read_b64 v[212:213], v227 offset:64
	ds_read_b64 v[214:215], v226 offset:96
	ds_read_b64 v[216:217], v227 offset:96
	v_lshl_add_u32 v218, v96, 2, v225
	v_add_u32_e32 v219, 0x4400, v218
	ds_read2_b32 v[220:221], v219 offset1:16
	ds_read2_b32 v[222:223], v219 offset0:32 offset1:48
	s_waitcnt lgkmcnt(12)
	v_mfma_f32_16x16x16_bf16 v[68:71], v[68:69], v[180:181], 0
	v_add3_u32 v193, v91, v144, v133
	v_add_u32_e32 v202, 0x2c00, v193
	v_add_u32_e32 v91, v91, v112
	v_mfma_f32_16x16x16_bf16 v[194:197], v[92:93], v[64:65], 0
	v_readlane_b32 s80, v247, 14
	v_readlane_b32 s81, v247, 15
	v_readlane_b32 s82, v247, 16
	s_waitcnt lgkmcnt(10)
	v_mfma_f32_16x16x16_bf16 v[62:65], v[198:199], v[64:65], v[68:71]
	v_readlane_b32 s83, v247, 17
	s_mov_b32 s81, s80
	s_mov_b32 s82, s80
	v_mfma_f32_16x16x16_bf16 v[68:71], v[94:95], v[56:57], v[194:197]
	ds_read2_b64 v[92:95], v51 offset0:8 offset1:12
	v_add_u32_e32 v51, 0x2000, v193
	s_mov_b32 s83, s80
	s_waitcnt lgkmcnt(0)
	v_mfma_f32_16x16x16_bf16 v[68:71], v[92:93], v[52:53], v[68:71]
	ds_read2_b64 v[194:197], v147 offset1:80
	v_writelane_b32 v247, s80, 14
	v_mfma_f32_16x16x16_bf16 v[68:71], v[94:95], v[48:49], v[68:71]
	ds_read2_b64 v[92:95], v50 offset0:40 offset1:44
	v_writelane_b32 v247, s81, 15
	v_writelane_b32 v247, s82, 16
	v_mfma_f32_16x16x16_bf16 v[198:201], v[200:201], v[56:57], v[62:65]
	v_writelane_b32 v247, s83, 17
	s_nop 2
	v_pk_mul_f32 v[56:57], v[60:61], v[70:71]
	v_pk_mul_f32 v[54:55], v[58:59], v[68:69]
	ds_read2_b64 v[62:65], v51 offset0:128 offset1:208
	ds_read2_b64 v[68:71], v202 offset0:64 offset1:144
	s_waitcnt lgkmcnt(3)
	v_mfma_f32_16x16x16_bf16 v[54:57], v[196:197], v[180:181], v[54:57]
	s_movk_i32 s80, 0x4540
	s_nop 6
	v_cvt_pk_bf16_f32 v50, v54, v55
	v_cvt_pk_bf16_f32 v51, v56, v57
	s_nop 1
	v_mfma_f32_16x16x16_bf16 v[54:57], v[194:195], v[50:51], 0
	s_nop 7
	v_pk_mul_f32 v[50:51], v[58:59], v[54:55]
	v_pk_mul_f32 v[58:59], v[60:61], v[56:57]
	v_cvt_pk_bf16_f32 v202, v50, v51
	s_waitcnt lgkmcnt(2)
	v_mfma_f32_16x16x16_bf16 v[50:53], v[92:93], v[52:53], v[198:201]
	v_cvt_pk_bf16_f32 v203, v58, v59
	v_cvt_pk_bf16_f32 v204, v54, v55
	v_add_u32_e32 v54, 0x2800, v193
	s_waitcnt lgkmcnt(1)
	v_mfma_f32_16x16x16_bf16 v[40:43], v[62:63], v[202:203], v[40:43]
	v_cvt_pk_bf16_f32 v205, v56, v57
	ds_read_b128 v[60:63], v91 offset:16896
	ds_read_b128 v[56:59], v91 offset:16960
	ds_read2_b64 v[194:197], v54 offset0:32 offset1:112
	v_mfma_f32_16x16x16_bf16 v[92:95], v[94:95], v[48:49], v[50:53]
	v_add_u32_e32 v54, 0x3000, v193
	ds_read2_b64 v[198:201], v54 offset0:96 offset1:176
	s_nop 0
	ds_read_b128 v[52:55], v91 offset:17024
	ds_read_b128 v[48:51], v91 offset:17088
	v_add_u32_e32 v91, s74, v174
	s_waitcnt lgkmcnt(6)
	v_mfma_f32_16x16x16_bf16 v[40:43], v[68:69], v[180:181], v[40:43]
	v_mfma_f32_16x16x16_bf16 v[66:69], v[66:67], v[204:205], v[92:95]
	v_mfma_f32_16x16x16_bf16 v[44:47], v[64:65], v[202:203], v[44:47]
	s_andn2_b64 vcc, exec, s[20:21]
	s_cbranch_vccnz .Lyold_done_b
	s_waitcnt vmcnt(0)
	v_lshlrev_b32_e32 v87, 16, v230
	v_lshlrev_b32_e32 v88, 16, v231
	v_lshlrev_b32_e32 v86, 16, v232
	v_lshlrev_b32_e32 v89, 16, v233
; #define MFMA4(a, b, c) __builtin_amdgcn_mfma_f32_16x16x16bf16_1k(a, b, c, 0, 0, 0)
; __device__ __forceinline__ void scan_pc(const Params& p, int j, const u16* R, const u16* K, const u16* V, u16* Y, u16* YB) {
;     ...
;       u16* IMG = shm + (c % 3) * IMG_ELEMS;
;       u16* MM = shm + 4 * IMG_ELEMS + (c & 1) * MM_ELEMS;
;       int ai = (w4 < 2) ? 0 : 1, bi = (w4 & 1) ? 3 : 2;
;       f32x4 mt = {0.f, 0.f, 0.f, 0.f}, nc = {0.f, 0.f, 0.f, 0.f};
;       _Pragma("unroll") for (int kb = 0; kb < 4; ++kb) {
;         s4 xa = *reinterpret_cast<const s4*>(IMG + (ai * 16 + fr) * XT_LD + kb * 16 + fq * 4);
;         s4 xb = *reinterpret_cast<const s4*>(IMG + (bi * 16 + fr) * XT_LD + kb * 16 + fq * 4);
;         mt = MFMA4(xb, xa, mt);
;         if (w4 == 0) nc = MFMA4(xa, xb, nc);
;       }
;       float* SSQ = reinterpret_cast<float*>(IMG + IMG_PL) + 128;
;       float inv_t = rsqrtf(fmaxf((SSQ[fr] + SSQ[16 + fr]) + (SSQ[32 + fr] + SSQ[48 + fr]), 1e-24f));
;       if (w4 == 3) SSQ[64 + fr] = inv_t;
;       float ivr = (w4 < 2) ? inv_t : 1.f;
;       float sc_[4];
;       _Pragma("unroll") for (int jj = 0; jj < 4; ++jj) {
;         float ivj = __builtin_bit_cast(float, __builtin_amdgcn_ds_bpermute(((lane & 48) | (fq * 4 + jj)) << 2, __builtin_bit_cast(int, inv_t)));
;         sc_[jj] = ivr * (((w4 & 1) == 0) ? ivj : 1.f);
;         mt[jj] *= sc_[jj] * keepm[jj];
;       }
;       if (w4 == 0) {
;         _Pragma("unroll") for (int jj = 0; jj < 4; ++jj) nc[jj] *= sc_[jj] * keepn[jj];
;         f32x4 z4 = {0.f, 0.f, 0.f, 0.f};
;         s4 pN = pack4v(nc), pNT = pack4v(mt);
;         f32x4 n2 = MFMA4(pNT, pN, z4);
;         f32x4 n2t = MFMA4(pN, pNT, z4);
;         s4 pN2 = pack4v(n2), pN2T = pack4v(n2t);
;         f32x4 n4 = MFMA4(pN2T, pN2, z4);
;         f32x4 n4t = MFMA4(pN2, pN2T, z4);
;         s4 pN4 = pack4v(n4), pN4T = pack4v(n4t);
;         f32x4 n8 = MFMA4(pN4T, pN4, z4);
;         s4 pN8 = pack4v(n8);
;         f32x4 tt = mt;
;         _Pragma("unroll") for (int jj = 0; jj < 4; ++jj) tt[jj] += diagm[jj];
;         tt = MFMA4(pN2, pack4v(tt), tt);
;         tt = MFMA4(pN4, pack4v(tt), tt);
;         tt = MFMA4(pN8, pack4v(tt), tt);
;         mt = tt;
;     ...
;       _Pragma("unroll") for (int jj = 0; jj < 4; ++jj)
;         sto<u16>(Yw, (unsigned)(offK0[jj] + c * dK), f2b(ymode == 1 ? y[jj] + yo[jj] : y[jj]));
.Lyold_done_b:
	s_nop 1
	v_add_u32_e32 v94, 2, v90
	s_nop 3
	v_add_f32_e32 v92, v87, v66
	v_cndmask_b32_e64 v66, v66, v92, s[20:21]
	v_add_f32_e32 v65, v86, v67
	v_cvt_pk_bf16_f32 v64, v66, s0
	v_cndmask_b32_e64 v65, v67, v65, s[20:21]
	s_waitcnt lgkmcnt(3)
	v_mfma_f32_16x16x16_bf16 v[32:35], v[194:195], v[202:203], v[32:35]
	global_store_short v91, v64, s[70:71]
	v_add_u32_e32 v64, s74, v173
	v_cvt_pk_bf16_f32 v65, v65, s0
	v_mfma_f32_16x16x16_bf16 v[36:39], v[196:197], v[202:203], v[36:39]
	global_store_short v64, v65, s[70:71]
	v_add_f32_e32 v65, v89, v68
	v_cndmask_b32_e64 v65, v68, v65, s[20:21]
	v_mfma_f32_16x16x16_bf16 v[44:47], v[70:71], v[180:181], v[44:47]
	v_add_u32_e32 v64, s74, v172
	v_cvt_pk_bf16_f32 v65, v65, s0
	global_store_short v64, v65, s[70:71]
	s_waitcnt lgkmcnt(2)
	v_mfma_f32_16x16x16_bf16 v[32:35], v[198:199], v[180:181], v[32:35]
	v_add_f32_e32 v64, v88, v69
	v_cndmask_b32_e64 v64, v69, v64, s[20:21]
	v_add_u32_e32 v65, s74, v171
	v_mfma_f32_16x16x16_bf16 v[36:39], v[200:201], v[180:181], v[36:39]
	v_cvt_pk_bf16_f32 v64, v64, s0
	v_cmp_gt_u32_e32 vcc, s2, v94
	global_store_short v65, v64, s[70:71]
	s_and_saveexec_b64 s[62:63], vcc
	s_cbranch_execz .LBB0_2763
	v_add_u32_e32 v64, s76, v90
	v_mad_u32_u24 v95, v64, s80, 0
	v_readlane_b32 s76, v247, 14
	v_readlane_b32 s77, v247, 15
	v_readlane_b32 s78, v247, 16
	v_readlane_b32 s79, v247, 17
	v_mov_b64_e32 v[68:69], s[76:77]
	s_waitcnt lgkmcnt(0)
	v_mfma_f32_16x16x16_bf16 v[64:67], v[234:235], v[236:237], 0
	v_mov_b64_e32 v[70:71], s[78:79]
	s_and_saveexec_b64 s[30:31], s[14:15]
	v_mfma_f32_16x16x16_bf16 v[68:71], v[236:237], v[234:235], 0
	s_or_b64 exec, exec, s[30:31]
	v_mfma_f32_16x16x16_bf16 v[64:67], v[206:207], v[208:209], v[64:67]
	s_and_saveexec_b64 s[30:31], s[14:15]
	v_mfma_f32_16x16x16_bf16 v[68:71], v[208:209], v[206:207], v[68:71]
	s_or_b64 exec, exec, s[30:31]
	v_mfma_f32_16x16x16_bf16 v[64:67], v[210:211], v[212:213], v[64:67]
	s_and_saveexec_b64 s[30:31], s[14:15]
	v_mfma_f32_16x16x16_bf16 v[68:71], v[212:213], v[210:211], v[68:71]
	s_or_b64 exec, exec, s[30:31]
	v_mfma_f32_16x16x16_bf16 v[64:67], v[214:215], v[216:217], v[64:67]
	s_and_saveexec_b64 s[30:31], s[14:15]
	v_mfma_f32_16x16x16_bf16 v[68:71], v[216:217], v[214:215], v[68:71]
	s_or_b64 exec, exec, s[30:31]
	v_lshl_add_u32 v91, v96, 2, v95
	s_waitcnt lgkmcnt(0)
	v_add_f32_e32 v179, v220, v221
	v_add_f32_e32 v90, v222, v223
	v_add_f32_e32 v90, v179, v90
	v_max_f32_e32 v90, 0x179abe15, v90
	v_rsq_f32_e32 v90, v90
	s_and_saveexec_b64 s[30:31], s[16:17]
	ds_write_b32 v91, v90 offset:17664
	s_or_b64 exec, exec, s[30:31]
	ds_bpermute_b32 v91, v138, v90
	ds_bpermute_b32 v92, v139, v90
	v_cndmask_b32_e64 v93, 1.0, v90, s[6:7]
	ds_bpermute_b32 v179, v140, v90
	ds_bpermute_b32 v224, v141, v90
	s_waitcnt lgkmcnt(3)
	v_cndmask_b32_e64 v91, 1.0, v91, s[18:19]
	s_waitcnt lgkmcnt(2)
	v_cndmask_b32_e64 v92, 1.0, v92, s[18:19]
	v_mul_f32_e32 v91, v93, v91
	v_mul_f32_e32 v180, v98, v91
	v_mul_f32_e32 v92, v93, v92
	v_mul_f32_e32 v64, v64, v180
	v_mul_f32_e32 v180, v101, v92
	v_mul_f32_e32 v65, v65, v180
	s_waitcnt lgkmcnt(1)
	v_cndmask_b32_e64 v90, 1.0, v179, s[18:19]
	v_mul_f32_e32 v90, v93, v90
	v_mul_f32_e32 v179, v104, v90
	v_mul_f32_e32 v66, v66, v179
	s_waitcnt lgkmcnt(0)
	v_cndmask_b32_e64 v179, 1.0, v224, s[18:19]
	v_mul_f32_e32 v93, v93, v179
	v_mul_f32_e32 v179, v107, v93
	v_mul_f32_e32 v67, v67, v179
	s_and_saveexec_b64 s[30:31], s[14:15]
	s_cbranch_execz .LBB0_2759
	v_mul_f32_e32 v91, v99, v91
	v_mul_f32_e32 v90, v105, v90
	v_mul_f32_e32 v68, v68, v91
	v_mul_f32_e32 v91, v102, v92
	v_mul_f32_e32 v70, v70, v90
	v_mul_f32_e32 v90, v108, v93
	v_mul_f32_e32 v69, v69, v91
	v_mul_f32_e32 v71, v71, v90
	v_cvt_pk_bf16_f32 v90, v68, v69
	v_cvt_pk_bf16_f32 v91, v70, v71
	v_cvt_pk_bf16_f32 v92, v64, v65
	v_cvt_pk_bf16_f32 v93, v66, v67
	v_add_f32_e32 v64, v100, v64
	v_add_f32_e32 v65, v103, v65
	v_mfma_f32_16x16x16_bf16 v[68:71], v[92:93], v[90:91], 0
	v_add_f32_e32 v66, v106, v66
	v_add_f32_e32 v67, v109, v67
	v_mfma_f32_16x16x16_bf16 v[90:93], v[90:91], v[92:93], 0
	s_nop 4
	v_cvt_pk_bf16_f32 v180, v68, v69
	v_cvt_pk_bf16_f32 v181, v70, v71
	s_nop 0
	v_cvt_pk_bf16_f32 v90, v90, v91
	v_cvt_pk_bf16_f32 v91, v92, v93
	s_nop 1
	v_mfma_f32_16x16x16_bf16 v[68:71], v[90:91], v[180:181], 0
	v_mfma_f32_16x16x16_bf16 v[90:93], v[180:181], v[90:91], 0
	s_nop 6
	v_cvt_pk_bf16_f32 v194, v68, v69
	v_cvt_pk_bf16_f32 v195, v70, v71
	v_cvt_pk_bf16_f32 v68, v90, v91
	v_cvt_pk_bf16_f32 v69, v92, v93
	s_nop 1
	v_mfma_f32_16x16x16_bf16 v[68:71], v[68:69], v[194:195], 0
	s_nop 7
	v_cvt_pk_bf16_f32 v68, v68, v69
	v_cvt_pk_bf16_f32 v69, v70, v71
	v_cvt_pk_bf16_f32 v70, v64, v65
	v_cvt_pk_bf16_f32 v71, v66, v67
	s_nop 1
	v_mfma_f32_16x16x16_bf16 v[64:67], v[180:181], v[70:71], v[64:67]
	s_nop 7
	v_cvt_pk_bf16_f32 v70, v64, v65
	v_cvt_pk_bf16_f32 v71, v66, v67
	s_nop 1
	v_mfma_f32_16x16x16_bf16 v[64:67], v[194:195], v[70:71], v[64:67]
	s_nop 7
	v_cvt_pk_bf16_f32 v70, v64, v65
	v_cvt_pk_bf16_f32 v71, v66, v67
	s_nop 1
	v_mfma_f32_16x16x16_bf16 v[64:67], v[68:69], v[70:71], v[64:67]
